# scan1pf: SCAN1 issues the 2nd/3rd batches of segment loads together with the first (fresh registers, def-use renamed)
# speedup vs baseline: 1.0016x; 1.0016x over previous
; __device__ __forceinline__ int obid() { int t = blockIdx.x; asm volatile("" : "+s"(t)); return t; }
; __device__ __forceinline__ void scan1_phase(const Params& p, int dir) {
;     ...
;   for (int it = obid(); it < 256; it += gridDim.x) {
;     const int b = it >> 7, cgp = (it >> 5) & 3, seg = it & 31;
;     const int ch0 = cgp * 256 + lane * 4;
;     const size_t rb = (size_t)b * TPB;
;     const int pos0 = seg * 264 + w * 33;
;     float h[4] = {0.f, 0.f, 0.f, 0.f}, as[4] = {0.f, 0.f, 0.f, 0.f};
;     {
;       uint4 v[33];
; #pragma unroll
;       for (int i = 0; i < 33; ++i) v[i] = *(const uint4*)(RG + (rb + scan_tok(dir, pos0 + i)) * D + ch0);
.LBB0_145:
	s_and_b32 s5, s2, 31
	s_mul_i32 s6, s5, 0x108
	v_add_u32_e32 v68, s6, v74
	v_cmp_lt_i32_e64 s[40:41], s81, v68
	s_ashr_i32 s3, s2, 7
	s_bfe_u32 s4, s2, 0x20005
	v_cndmask_b32_e64 v0, v222, v223, s[40:41]
	v_sub_u32_e32 v0, v0, v68
	v_cndmask_b32_e32 v0, v68, v0, vcc
	v_ashrrev_i32_e32 v1, 31, v0
	v_lshl_or_b32 v166, s4, 10, v75
	v_mad_i64_i32 v[0:1], s[6:7], s3, v224, v[0:1]
	v_lshl_add_u64 v[46:47], s[42:43], 0, v[166:167]
	v_lshlrev_b64 v[0:1], 12, v[0:1]
	v_cmp_gt_i32_e64 s[40:41], s81, v68
	v_lshl_add_u64 v[66:67], v[46:47], 0, v[0:1]
	v_add_u32_e32 v0, 1, v68
	v_cndmask_b32_e64 v1, v223, v222, s[40:41]
	v_sub_u32_e32 v1, v1, v0
	v_cndmask_b32_e32 v0, v0, v1, vcc
	v_ashrrev_i32_e32 v1, 31, v0
	v_mad_i64_i32 v[0:1], s[6:7], s3, v224, v[0:1]
	v_lshlrev_b64 v[0:1], 12, v[0:1]
	v_cmp_lt_i32_e64 s[40:41], s8, v68
	v_lshl_add_u64 v[50:51], v[46:47], 0, v[0:1]
	v_add_u32_e32 v0, 2, v68
	v_cndmask_b32_e64 v1, v222, v223, s[40:41]
	v_sub_u32_e32 v1, v1, v0
	v_cndmask_b32_e32 v0, v0, v1, vcc
	v_ashrrev_i32_e32 v1, 31, v0
	v_mad_i64_i32 v[0:1], s[6:7], s3, v224, v[0:1]
	v_lshlrev_b64 v[0:1], 12, v[0:1]
	v_cmp_lt_i32_e64 s[40:41], s9, v68
	v_lshl_add_u64 v[38:39], v[46:47], 0, v[0:1]
	v_add_u32_e32 v0, 3, v68
	v_cndmask_b32_e64 v1, v222, v223, s[40:41]
	v_sub_u32_e32 v1, v1, v0
	v_cndmask_b32_e32 v0, v0, v1, vcc
	v_ashrrev_i32_e32 v1, 31, v0
	v_mad_i64_i32 v[0:1], s[6:7], s3, v224, v[0:1]
	v_lshlrev_b64 v[0:1], 12, v[0:1]
	v_cmp_lt_i32_e64 s[40:41], s10, v68
	v_lshl_add_u64 v[48:49], v[46:47], 0, v[0:1]
	v_add_u32_e32 v0, 4, v68
	v_cndmask_b32_e64 v1, v222, v223, s[40:41]
	v_sub_u32_e32 v1, v1, v0
	v_cndmask_b32_e32 v0, v0, v1, vcc
	v_ashrrev_i32_e32 v1, 31, v0
	v_mad_i64_i32 v[0:1], s[6:7], s3, v224, v[0:1]
	v_lshlrev_b64 v[0:1], 12, v[0:1]
	v_cmp_lt_i32_e64 s[40:41], s11, v68
	v_lshl_add_u64 v[52:53], v[46:47], 0, v[0:1]
	v_add_u32_e32 v0, 5, v68
	v_cndmask_b32_e64 v1, v222, v223, s[40:41]
	v_sub_u32_e32 v1, v1, v0
	v_cndmask_b32_e32 v0, v0, v1, vcc
	v_ashrrev_i32_e32 v1, 31, v0
	v_mad_i64_i32 v[0:1], s[6:7], s3, v224, v[0:1]
	v_lshlrev_b64 v[0:1], 12, v[0:1]
	v_cmp_lt_i32_e64 s[40:41], s12, v68
	v_lshl_add_u64 v[54:55], v[46:47], 0, v[0:1]
	v_add_u32_e32 v0, 6, v68
	v_cndmask_b32_e64 v1, v222, v223, s[40:41]
	v_sub_u32_e32 v1, v1, v0
	v_cndmask_b32_e32 v0, v0, v1, vcc
	v_ashrrev_i32_e32 v1, 31, v0
	v_mad_i64_i32 v[0:1], s[6:7], s3, v224, v[0:1]
	v_lshlrev_b64 v[0:1], 12, v[0:1]
	v_cmp_lt_i32_e64 s[40:41], s13, v68
	v_lshl_add_u64 v[56:57], v[46:47], 0, v[0:1]
	v_add_u32_e32 v0, 7, v68
	v_cndmask_b32_e64 v1, v222, v223, s[40:41]
	v_sub_u32_e32 v1, v1, v0
	v_cndmask_b32_e32 v0, v0, v1, vcc
	v_ashrrev_i32_e32 v1, 31, v0
	v_mad_i64_i32 v[0:1], s[6:7], s3, v224, v[0:1]
	v_lshlrev_b64 v[0:1], 12, v[0:1]
	v_cmp_lt_i32_e64 s[40:41], s14, v68
	v_lshl_add_u64 v[58:59], v[46:47], 0, v[0:1]
	v_add_u32_e32 v0, 8, v68
	v_cndmask_b32_e64 v1, v222, v223, s[40:41]
	v_sub_u32_e32 v1, v1, v0
	v_cndmask_b32_e32 v0, v0, v1, vcc
	v_ashrrev_i32_e32 v1, 31, v0
	v_mad_i64_i32 v[0:1], s[6:7], s3, v224, v[0:1]
	v_lshlrev_b64 v[0:1], 12, v[0:1]
	v_cmp_lt_i32_e64 s[40:41], s15, v68
	v_lshl_add_u64 v[60:61], v[46:47], 0, v[0:1]
	v_add_u32_e32 v0, 9, v68
	v_cndmask_b32_e64 v1, v222, v223, s[40:41]
	v_sub_u32_e32 v1, v1, v0
	v_cndmask_b32_e32 v0, v0, v1, vcc
	v_ashrrev_i32_e32 v1, 31, v0
	v_mad_i64_i32 v[0:1], s[6:7], s3, v224, v[0:1]
	v_lshlrev_b64 v[0:1], 12, v[0:1]
	v_cmp_lt_i32_e64 s[40:41], s16, v68
	v_lshl_add_u64 v[62:63], v[46:47], 0, v[0:1]
	v_add_u32_e32 v0, 10, v68
	v_cndmask_b32_e64 v1, v222, v223, s[40:41]
	v_sub_u32_e32 v1, v1, v0
	v_cndmask_b32_e32 v0, v0, v1, vcc
	v_ashrrev_i32_e32 v1, 31, v0
	v_mad_i64_i32 v[0:1], s[6:7], s3, v224, v[0:1]
	s_movk_i32 s6, 0xf4
	v_lshlrev_b64 v[0:1], 12, v[0:1]
	v_cmp_lt_i32_e64 s[40:41], s6, v68
	v_lshl_add_u64 v[64:65], v[46:47], 0, v[0:1]
	v_add_u32_e32 v0, 11, v68
	v_cndmask_b32_e64 v1, v222, v223, s[40:41]
	v_sub_u32_e32 v1, v1, v0
	v_cndmask_b32_e32 v0, v0, v1, vcc
	v_ashrrev_i32_e32 v1, 31, v0
	v_mad_i64_i32 v[0:1], s[6:7], s3, v224, v[0:1]
	s_movk_i32 s6, 0xf3
	v_lshlrev_b64 v[0:1], 12, v[0:1]
	v_cmp_lt_i32_e64 s[40:41], s6, v68
	v_lshl_add_u64 v[20:21], v[46:47], 0, v[0:1]
	v_add_u32_e32 v0, 12, v68
	v_cndmask_b32_e64 v1, v222, v223, s[40:41]
	v_sub_u32_e32 v1, v1, v0
	v_cndmask_b32_e32 v0, v0, v1, vcc
	v_ashrrev_i32_e32 v1, 31, v0
	v_mad_i64_i32 v[0:1], s[6:7], s3, v224, v[0:1]
	s_movk_i32 s6, 0xf2
	v_lshlrev_b64 v[0:1], 12, v[0:1]
	v_cmp_lt_i32_e64 s[40:41], s6, v68
	v_lshl_add_u64 v[16:17], v[46:47], 0, v[0:1]
	v_add_u32_e32 v0, 13, v68
	v_cndmask_b32_e64 v1, v222, v223, s[40:41]
	v_sub_u32_e32 v1, v1, v0
	v_cndmask_b32_e32 v0, v0, v1, vcc
	v_ashrrev_i32_e32 v1, 31, v0
	v_mad_i64_i32 v[0:1], s[6:7], s3, v224, v[0:1]
	s_movk_i32 s6, 0xf1
	v_lshlrev_b64 v[0:1], 12, v[0:1]
	v_cmp_lt_i32_e64 s[40:41], s6, v68
	v_lshl_add_u64 v[18:19], v[46:47], 0, v[0:1]
	v_add_u32_e32 v0, 14, v68
	v_cndmask_b32_e64 v1, v222, v223, s[40:41]
	v_sub_u32_e32 v1, v1, v0
	v_cndmask_b32_e32 v0, v0, v1, vcc
	v_ashrrev_i32_e32 v1, 31, v0
	v_mad_i64_i32 v[0:1], s[6:7], s3, v224, v[0:1]
	s_movk_i32 s6, 0xf0
	v_lshlrev_b64 v[0:1], 12, v[0:1]
	v_cmp_lt_i32_e64 s[40:41], s6, v68
	v_lshl_add_u64 v[22:23], v[46:47], 0, v[0:1]
	v_add_u32_e32 v0, 15, v68
	v_cndmask_b32_e64 v1, v222, v223, s[40:41]
	v_sub_u32_e32 v1, v1, v0
	v_cndmask_b32_e32 v0, v0, v1, vcc
	v_ashrrev_i32_e32 v1, 31, v0
	v_mad_i64_i32 v[0:1], s[6:7], s3, v224, v[0:1]
	s_movk_i32 s6, 0xef
	v_lshlrev_b64 v[0:1], 12, v[0:1]
	v_cmp_lt_i32_e64 s[40:41], s6, v68
	v_lshl_add_u64 v[24:25], v[46:47], 0, v[0:1]
	v_add_u32_e32 v0, 16, v68
	v_cndmask_b32_e64 v1, v222, v223, s[40:41]
; __device__ __forceinline__ void scan1_phase(const Params& p, int dir) {
;     ...
;     const int pos0 = seg * 264 + w * 33;
;     float h[4] = {0.f, 0.f, 0.f, 0.f}, as[4] = {0.f, 0.f, 0.f, 0.f};
;     {
;       uint4 v[33];
; #pragma unroll
;       for (int i = 0; i < 33; ++i) v[i] = *(const uint4*)(RG + (rb + scan_tok(dir, pos0 + i)) * D + ch0);
	v_sub_u32_e32 v1, v1, v0
	v_cndmask_b32_e32 v0, v0, v1, vcc
	v_ashrrev_i32_e32 v1, 31, v0
	v_mad_i64_i32 v[0:1], s[6:7], s3, v224, v[0:1]
	s_movk_i32 s6, 0xee
	v_lshlrev_b64 v[0:1], 12, v[0:1]
	v_cmp_lt_i32_e64 s[40:41], s6, v68
	v_lshl_add_u64 v[26:27], v[46:47], 0, v[0:1]
	v_add_u32_e32 v0, 17, v68
	v_cndmask_b32_e64 v1, v222, v223, s[40:41]
	v_sub_u32_e32 v1, v1, v0
	v_cndmask_b32_e32 v0, v0, v1, vcc
	v_ashrrev_i32_e32 v1, 31, v0
	v_mad_i64_i32 v[0:1], s[6:7], s3, v224, v[0:1]
	s_movk_i32 s6, 0xed
	v_lshlrev_b64 v[0:1], 12, v[0:1]
	v_cmp_lt_i32_e64 s[40:41], s6, v68
	v_lshl_add_u64 v[28:29], v[46:47], 0, v[0:1]
	v_add_u32_e32 v0, 18, v68
	v_cndmask_b32_e64 v1, v222, v223, s[40:41]
	v_sub_u32_e32 v1, v1, v0
	v_cndmask_b32_e32 v0, v0, v1, vcc
	v_ashrrev_i32_e32 v1, 31, v0
	v_mad_i64_i32 v[0:1], s[6:7], s3, v224, v[0:1]
	s_movk_i32 s6, 0xec
	v_lshlrev_b64 v[0:1], 12, v[0:1]
	v_cmp_lt_i32_e64 s[40:41], s6, v68
	v_lshl_add_u64 v[30:31], v[46:47], 0, v[0:1]
	v_add_u32_e32 v0, 19, v68
	v_cndmask_b32_e64 v1, v222, v223, s[40:41]
	v_sub_u32_e32 v1, v1, v0
	v_cndmask_b32_e32 v0, v0, v1, vcc
	v_ashrrev_i32_e32 v1, 31, v0
	v_mad_i64_i32 v[0:1], s[6:7], s3, v224, v[0:1]
	s_movk_i32 s6, 0xeb
	v_lshlrev_b64 v[0:1], 12, v[0:1]
	v_cmp_lt_i32_e64 s[40:41], s6, v68
	v_lshl_add_u64 v[32:33], v[46:47], 0, v[0:1]
	v_add_u32_e32 v0, 20, v68
	v_cndmask_b32_e64 v1, v222, v223, s[40:41]
	v_sub_u32_e32 v1, v1, v0
	v_cndmask_b32_e32 v0, v0, v1, vcc
	v_ashrrev_i32_e32 v1, 31, v0
	v_mad_i64_i32 v[0:1], s[6:7], s3, v224, v[0:1]
	s_movk_i32 s6, 0xea
	v_lshlrev_b64 v[0:1], 12, v[0:1]
	v_cmp_lt_i32_e64 s[40:41], s6, v68
	v_lshl_add_u64 v[34:35], v[46:47], 0, v[0:1]
	v_add_u32_e32 v0, 21, v68
	v_cndmask_b32_e64 v1, v222, v223, s[40:41]
	v_sub_u32_e32 v1, v1, v0
	v_cndmask_b32_e32 v0, v0, v1, vcc
	v_ashrrev_i32_e32 v1, 31, v0
	v_mad_i64_i32 v[0:1], s[6:7], s3, v224, v[0:1]
	s_movk_i32 s6, 0xe9
	v_lshlrev_b64 v[0:1], 12, v[0:1]
	v_cmp_lt_i32_e64 s[40:41], s6, v68
	v_lshl_add_u64 v[36:37], v[46:47], 0, v[0:1]
	v_add_u32_e32 v0, 22, v68
	v_cndmask_b32_e64 v1, v222, v223, s[40:41]
	v_sub_u32_e32 v1, v1, v0
	v_cndmask_b32_e32 v0, v0, v1, vcc
	v_ashrrev_i32_e32 v1, 31, v0
	v_mad_i64_i32 v[0:1], s[6:7], s3, v224, v[0:1]
	s_movk_i32 s6, 0xe8
	v_lshlrev_b64 v[0:1], 12, v[0:1]
	v_cmp_lt_i32_e64 s[40:41], s6, v68
	v_lshl_add_u64 v[6:7], v[46:47], 0, v[0:1]
	v_add_u32_e32 v0, 23, v68
	v_cndmask_b32_e64 v1, v222, v223, s[40:41]
	v_sub_u32_e32 v1, v1, v0
	v_cndmask_b32_e32 v0, v0, v1, vcc
	v_ashrrev_i32_e32 v1, 31, v0
	v_mad_i64_i32 v[0:1], s[6:7], s3, v224, v[0:1]
	s_movk_i32 s6, 0xe7
	v_lshlrev_b64 v[0:1], 12, v[0:1]
	v_cmp_lt_i32_e64 s[40:41], s6, v68
	v_lshl_add_u64 v[2:3], v[46:47], 0, v[0:1]
	v_add_u32_e32 v0, 24, v68
	v_cndmask_b32_e64 v1, v222, v223, s[40:41]
	v_sub_u32_e32 v1, v1, v0
	v_cndmask_b32_e32 v0, v0, v1, vcc
	v_ashrrev_i32_e32 v1, 31, v0
	v_mad_i64_i32 v[0:1], s[6:7], s3, v224, v[0:1]
	s_movk_i32 s6, 0xe6
	s_nop 0
	v_cmp_lt_i32_e64 s[40:41], s6, v68
	v_add_u32_e32 v4, 25, v68
	v_add_u32_e32 v8, 26, v68
	v_cndmask_b32_e64 v5, v222, v223, s[40:41]
	v_sub_u32_e32 v5, v5, v4
	v_cndmask_b32_e32 v4, v4, v5, vcc
	v_ashrrev_i32_e32 v5, 31, v4
	v_mad_i64_i32 v[4:5], s[6:7], s3, v224, v[4:5]
	s_movk_i32 s6, 0xe5
	s_nop 0
	v_cmp_lt_i32_e64 s[40:41], s6, v68
	v_add_u32_e32 v10, 27, v68
	v_add_u32_e32 v12, 28, v68
	v_cndmask_b32_e64 v9, v222, v223, s[40:41]
	v_sub_u32_e32 v9, v9, v8
	v_cndmask_b32_e32 v8, v8, v9, vcc
	v_ashrrev_i32_e32 v9, 31, v8
	v_mad_i64_i32 v[8:9], s[6:7], s3, v224, v[8:9]
	s_movk_i32 s6, 0xe4
	s_nop 0
	v_cmp_lt_i32_e64 s[40:41], s6, v68
	v_add_u32_e32 v14, 29, v68
	v_add_u32_e32 v42, 30, v68
	v_cndmask_b32_e64 v11, v222, v223, s[40:41]
	v_sub_u32_e32 v11, v11, v10
	v_cndmask_b32_e32 v10, v10, v11, vcc
	v_ashrrev_i32_e32 v11, 31, v10
	v_mad_i64_i32 v[10:11], s[6:7], s3, v224, v[10:11]
	s_movk_i32 s6, 0xe3
	s_nop 0
	v_cmp_lt_i32_e64 s[40:41], s6, v68
	v_add_u32_e32 v44, 31, v68
	v_add_u32_e32 v69, 32, v68
	v_cndmask_b32_e64 v13, v222, v223, s[40:41]
	v_sub_u32_e32 v13, v13, v12
	v_cndmask_b32_e32 v12, v12, v13, vcc
	v_ashrrev_i32_e32 v13, 31, v12
	v_mad_i64_i32 v[12:13], s[6:7], s3, v224, v[12:13]
	s_movk_i32 s6, 0xe2
	s_nop 0
	v_cmp_lt_i32_e64 s[40:41], s6, v68
	v_lshlrev_b64 v[0:1], 12, v[0:1]
	v_lshlrev_b64 v[4:5], 12, v[4:5]
	v_cndmask_b32_e64 v15, v222, v223, s[40:41]
	v_sub_u32_e32 v15, v15, v14
	v_cndmask_b32_e32 v14, v14, v15, vcc
	v_ashrrev_i32_e32 v15, 31, v14
	v_mad_i64_i32 v[14:15], s[6:7], s3, v224, v[14:15]
	s_movk_i32 s6, 0xe1
	s_nop 0
	v_cmp_lt_i32_e64 s[40:41], s6, v68
	v_lshlrev_b64 v[8:9], 12, v[8:9]
	v_lshlrev_b64 v[10:11], 12, v[10:11]
	v_cndmask_b32_e64 v43, v222, v223, s[40:41]
	v_sub_u32_e32 v43, v43, v42
	v_cndmask_b32_e32 v42, v42, v43, vcc
	v_ashrrev_i32_e32 v43, 31, v42
	v_mad_i64_i32 v[42:43], s[6:7], s3, v224, v[42:43]
	s_movk_i32 s6, 0xe0
	s_nop 0
	v_cmp_lt_i32_e64 s[40:41], s6, v68
	v_lshlrev_b64 v[12:13], 12, v[12:13]
	v_lshlrev_b64 v[14:15], 12, v[14:15]
	v_cndmask_b32_e64 v45, v222, v223, s[40:41]
	v_sub_u32_e32 v45, v45, v44
	v_cndmask_b32_e32 v44, v44, v45, vcc
	v_ashrrev_i32_e32 v45, 31, v44
	v_mad_i64_i32 v[44:45], s[6:7], s3, v224, v[44:45]
	s_movk_i32 s6, 0xdf
	s_nop 0
	v_cmp_lt_i32_e64 s[40:41], s6, v68
	v_lshlrev_b64 v[42:43], 12, v[42:43]
	v_lshlrev_b64 v[44:45], 12, v[44:45]
	v_cndmask_b32_e64 v68, v222, v223, s[40:41]
	v_sub_u32_e32 v68, v68, v69
	v_cndmask_b32_e32 v68, v69, v68, vcc
	v_ashrrev_i32_e32 v69, 31, v68
	v_mad_i64_i32 v[68:69], s[6:7], s3, v224, v[68:69]
	v_lshlrev_b64 v[68:69], 12, v[68:69]
	v_lshl_add_u64 v[0:1], v[46:47], 0, v[0:1]
	v_lshl_add_u64 v[4:5], v[46:47], 0, v[4:5]
	v_lshl_add_u64 v[8:9], v[46:47], 0, v[8:9]
	v_lshl_add_u64 v[10:11], v[46:47], 0, v[10:11]
	v_lshl_add_u64 v[12:13], v[46:47], 0, v[12:13]
	v_lshl_add_u64 v[14:15], v[46:47], 0, v[14:15]
	v_lshl_add_u64 v[42:43], v[46:47], 0, v[42:43]
	v_lshl_add_u64 v[44:45], v[46:47], 0, v[44:45]
	v_lshl_add_u64 v[46:47], v[46:47], 0, v[68:69]
	global_load_dwordx4 v[66:69], v[66:67], off
	s_lshl_b32 s3, s3, 2
	s_lshl_b32 s30, s5, 3
	s_or_b32 s3, s3, s4
	s_add_i32 s2, s2, s80
	s_cmpk_gt_i32 s2, 0xff
	s_waitcnt vmcnt(0)
; __device__ __forceinline__ float lo2f(uint32_t u) { return __uint_as_float(u << 16); }
; __device__ __forceinline__ void scan1_phase(const Params& p, int dir) {
;     ...
; #pragma unroll
;       for (int i = 0; i < 33; ++i) v[i] = *(const uint4*)(RG + (rb + scan_tok(dir, pos0 + i)) * D + ch0);
; #pragma unroll
;       for (int i = 0; i < 33; ++i) {
;         scan_step4(v[i], h);
;         as[0] += lo2f(v[i].x); as[1] += lo2f(v[i].y); as[2] += lo2f(v[i].z); as[3] += lo2f(v[i].w);
;       }
	v_lshlrev_b32_e32 v93, 16, v67
	v_lshlrev_b32_e32 v92, 16, v66
	v_and_b32_e32 v96, 0xffff0000, v66
	v_mul_f32_e32 v66, 0x3fb8aa3b, v93
	v_lshlrev_b32_e32 v98, 16, v68
	v_exp_f32_e32 v95, v66
	v_lshlrev_b32_e32 v99, 16, v69
	v_mul_f32_e32 v66, 0x3fb8aa3b, v98
	v_exp_f32_e32 v100, v66
	v_mul_f32_e32 v66, 0x3fb8aa3b, v99
	v_and_b32_e32 v97, 0xffff0000, v67
	v_and_b32_e32 v102, 0xffff0000, v68
	v_exp_f32_e32 v101, v66
	v_and_b32_e32 v103, 0xffff0000, v69
	global_load_dwordx4 v[66:69], v[50:51], off
	v_mul_f32_e32 v70, 0x3fb8aa3b, v92
	v_exp_f32_e32 v94, v70
	global_load_dwordx4 v[70:73], v[38:39], off
	global_load_dwordx4 v[76:79], v[48:49], off
	s_nop 0
	global_load_dwordx4 v[50:53], v[52:53], off
	s_nop 0
	global_load_dwordx4 v[80:83], v[54:55], off
	s_nop 0
	global_load_dwordx4 v[54:57], v[56:57], off
	s_nop 0
	global_load_dwordx4 v[84:87], v[58:59], off
	s_nop 0
	global_load_dwordx4 v[58:61], v[60:61], off
	s_nop 0
	global_load_dwordx4 v[88:91], v[62:63], off
	s_nop 0
	global_load_dwordx4 v[62:65], v[64:65], off
	global_load_dwordx4 v[114:117], v[20:21], off
	global_load_dwordx4 v[118:121], v[16:17], off
	global_load_dwordx4 v[122:125], v[18:19], off
	global_load_dwordx4 v[126:129], v[22:23], off
	global_load_dwordx4 v[130:133], v[24:25], off
	global_load_dwordx4 v[134:137], v[26:27], off
	global_load_dwordx4 v[138:141], v[28:29], off
	global_load_dwordx4 v[142:145], v[30:31], off
	global_load_dwordx4 v[146:149], v[32:33], off
	global_load_dwordx4 v[150:153], v[34:35], off
	global_load_dwordx4 v[154:157], v[36:37], off
	global_load_dwordx4 v[158:161], v[6:7], off
	global_load_dwordx4 v[178:181], v[2:3], off
	global_load_dwordx4 v[182:185], v[0:1], off
	global_load_dwordx4 v[186:189], v[4:5], off
	global_load_dwordx4 v[190:193], v[8:9], off
	global_load_dwordx4 v[194:197], v[10:11], off
	global_load_dwordx4 v[198:201], v[12:13], off
	global_load_dwordx4 v[202:205], v[14:15], off
	global_load_dwordx4 v[206:209], v[42:43], off
	global_load_dwordx4 v[210:213], v[44:45], off
	global_load_dwordx4 v[236:239], v[46:47], off
	v_pk_add_f32 v[38:39], v[92:93], 0 op_sel_hi:[1,0]
	v_pk_fma_f32 v[94:95], v[94:95], 0, v[96:97] op_sel_hi:[1,0,1]
	s_waitcnt vmcnt(30)
	v_lshlrev_b32_e32 v93, 16, v71
	v_lshlrev_b32_e32 v92, 16, v70
	v_lshlrev_b32_e32 v105, 16, v67
	v_lshlrev_b32_e32 v104, 16, v66
	v_mul_f32_e32 v48, 0x3fb8aa3b, v104
	v_mul_f32_e32 v49, 0x3fb8aa3b, v105
	v_pk_add_f32 v[38:39], v[38:39], v[104:105]
	v_exp_f32_e32 v48, v48
	v_exp_f32_e32 v49, v49
	v_mul_f32_e32 v104, 0x3fb8aa3b, v92
	v_mul_f32_e32 v105, 0x3fb8aa3b, v93
	v_pk_add_f32 v[38:39], v[38:39], v[92:93]
	s_waitcnt vmcnt(29)
	v_lshlrev_b32_e32 v93, 16, v77
	v_lshlrev_b32_e32 v92, 16, v76
	v_exp_f32_e32 v104, v104
	v_exp_f32_e32 v105, v105
	v_mul_f32_e32 v108, 0x3fb8aa3b, v92
	v_mul_f32_e32 v109, 0x3fb8aa3b, v93
	v_exp_f32_e32 v108, v108
	v_exp_f32_e32 v109, v109
	v_pk_add_f32 v[38:39], v[38:39], v[92:93]
	s_waitcnt vmcnt(28)
	v_lshlrev_b32_e32 v93, 16, v51
	v_lshlrev_b32_e32 v92, 16, v50
	v_and_b32_e32 v67, 0xffff0000, v67
	v_and_b32_e32 v66, 0xffff0000, v66
	v_mul_f32_e32 v110, 0x3fb8aa3b, v92
	v_mul_f32_e32 v111, 0x3fb8aa3b, v93
	v_pk_fma_f32 v[48:49], v[94:95], v[48:49], v[66:67]
	v_and_b32_e32 v67, 0xffff0000, v71
	v_and_b32_e32 v66, 0xffff0000, v70
	v_exp_f32_e32 v110, v110
	v_exp_f32_e32 v111, v111
	v_pk_add_f32 v[38:39], v[38:39], v[92:93]
	s_waitcnt vmcnt(27)
	v_lshlrev_b32_e32 v93, 16, v81
	v_lshlrev_b32_e32 v92, 16, v80
	v_pk_fma_f32 v[48:49], v[48:49], v[104:105], v[66:67]
	v_and_b32_e32 v67, 0xffff0000, v77
	v_and_b32_e32 v66, 0xffff0000, v76
	v_mul_f32_e32 v112, 0x3fb8aa3b, v92
	v_mul_f32_e32 v113, 0x3fb8aa3b, v93
	v_pk_fma_f32 v[48:49], v[48:49], v[108:109], v[66:67]
	v_pk_add_f32 v[38:39], v[38:39], v[92:93]
	s_waitcnt vmcnt(26)
	v_lshlrev_b32_e32 v67, 16, v55
	v_lshlrev_b32_e32 v66, 16, v54
	v_exp_f32_e32 v112, v112
	v_exp_f32_e32 v113, v113
	v_mul_f32_e32 v70, 0x3fb8aa3b, v66
	v_mul_f32_e32 v71, 0x3fb8aa3b, v67
	v_pk_add_f32 v[38:39], v[38:39], v[66:67]
	s_waitcnt vmcnt(25)
	v_lshlrev_b32_e32 v67, 16, v85
	v_lshlrev_b32_e32 v66, 16, v84
	v_and_b32_e32 v51, 0xffff0000, v51
	v_and_b32_e32 v50, 0xffff0000, v50
	v_exp_f32_e32 v70, v70
	v_exp_f32_e32 v71, v71
	v_mul_f32_e32 v76, 0x3fb8aa3b, v66
	v_mul_f32_e32 v77, 0x3fb8aa3b, v67
	v_pk_add_f32 v[38:39], v[38:39], v[66:67]
	s_waitcnt vmcnt(24)
	v_lshlrev_b32_e32 v67, 16, v59
	v_lshlrev_b32_e32 v66, 16, v58
	v_pk_fma_f32 v[48:49], v[48:49], v[110:111], v[50:51]
	v_and_b32_e32 v51, 0xffff0000, v81
	v_and_b32_e32 v50, 0xffff0000, v80
	v_exp_f32_e32 v76, v76
	v_exp_f32_e32 v77, v77
	v_mul_f32_e32 v80, 0x3fb8aa3b, v66
	v_mul_f32_e32 v81, 0x3fb8aa3b, v67
	v_pk_add_f32 v[38:39], v[38:39], v[66:67]
	s_waitcnt vmcnt(23)
	v_lshlrev_b32_e32 v67, 16, v89
	v_lshlrev_b32_e32 v66, 16, v88
	v_exp_f32_e32 v80, v80
	v_exp_f32_e32 v81, v81
	v_mul_f32_e32 v92, 0x3fb8aa3b, v66
	v_mul_f32_e32 v93, 0x3fb8aa3b, v67
	s_waitcnt vmcnt(22)
; __device__ __forceinline__ float lo2f(uint32_t u) { return __uint_as_float(u << 16); }
; __device__ __forceinline__ void scan1_phase(const Params& p, int dir) {
;     ...
; #pragma unroll
;       for (int i = 0; i < 33; ++i) v[i] = *(const uint4*)(RG + (rb + scan_tok(dir, pos0 + i)) * D + ch0);
; #pragma unroll
;       for (int i = 0; i < 33; ++i) {
;         scan_step4(v[i], h);
;         as[0] += lo2f(v[i].x); as[1] += lo2f(v[i].y); as[2] += lo2f(v[i].z); as[3] += lo2f(v[i].w);
;       }
	v_lshlrev_b32_e32 v95, 16, v63
	v_lshlrev_b32_e32 v94, 16, v62
	v_exp_f32_e32 v92, v92
	v_exp_f32_e32 v93, v93
	v_pk_add_f32 v[66:67], v[38:39], v[66:67]
	v_mul_f32_e32 v38, 0x3fb8aa3b, v94
	v_mul_f32_e32 v39, 0x3fb8aa3b, v95
	v_pk_fma_f32 v[48:49], v[48:49], v[112:113], v[50:51]
	v_and_b32_e32 v51, 0xffff0000, v55
	v_and_b32_e32 v50, 0xffff0000, v54
	v_exp_f32_e32 v38, v38
	v_exp_f32_e32 v39, v39
	v_pk_fma_f32 v[48:49], v[48:49], v[70:71], v[50:51]
	v_and_b32_e32 v51, 0xffff0000, v85
	v_and_b32_e32 v50, 0xffff0000, v84
	v_pk_fma_f32 v[48:49], v[48:49], v[76:77], v[50:51]
	v_and_b32_e32 v51, 0xffff0000, v59
	v_and_b32_e32 v50, 0xffff0000, v58
	v_pk_fma_f32 v[48:49], v[48:49], v[80:81], v[50:51]
	v_and_b32_e32 v51, 0xffff0000, v89
	v_and_b32_e32 v50, 0xffff0000, v88
	v_pk_fma_f32 v[48:49], v[48:49], v[92:93], v[50:51]
	v_and_b32_e32 v51, 0xffff0000, v63
	v_and_b32_e32 v50, 0xffff0000, v62
	v_lshlrev_b32_e32 v107, 16, v69
	v_lshlrev_b32_e32 v106, 16, v68
	v_pk_fma_f32 v[38:39], v[48:49], v[38:39], v[50:51]
	v_pk_add_f32 v[48:49], v[98:99], 0 op_sel_hi:[1,0]
	v_mul_f32_e32 v54, 0x3fb8aa3b, v106
	v_mul_f32_e32 v55, 0x3fb8aa3b, v107
	v_pk_add_f32 v[48:49], v[48:49], v[106:107]
	v_lshlrev_b32_e32 v59, 16, v73
	v_lshlrev_b32_e32 v58, 16, v72
	v_exp_f32_e32 v54, v54
	v_exp_f32_e32 v55, v55
	v_mul_f32_e32 v62, 0x3fb8aa3b, v58
	v_mul_f32_e32 v63, 0x3fb8aa3b, v59
	v_pk_add_f32 v[48:49], v[48:49], v[58:59]
	v_lshlrev_b32_e32 v59, 16, v79
	v_lshlrev_b32_e32 v58, 16, v78
	v_pk_add_f32 v[50:51], v[66:67], v[94:95]
	v_exp_f32_e32 v62, v62
	v_exp_f32_e32 v63, v63
	v_mul_f32_e32 v66, 0x3fb8aa3b, v58
	v_mul_f32_e32 v67, 0x3fb8aa3b, v59
	v_exp_f32_e32 v66, v66
	v_exp_f32_e32 v67, v67
	v_pk_add_f32 v[48:49], v[48:49], v[58:59]
	v_lshlrev_b32_e32 v59, 16, v53
	v_lshlrev_b32_e32 v58, 16, v52
	v_pk_fma_f32 v[80:81], v[100:101], 0, v[102:103] op_sel_hi:[1,0,1]
	v_and_b32_e32 v69, 0xffff0000, v69
	v_and_b32_e32 v68, 0xffff0000, v68
	v_mul_f32_e32 v70, 0x3fb8aa3b, v58
	v_mul_f32_e32 v71, 0x3fb8aa3b, v59
	v_pk_add_f32 v[48:49], v[48:49], v[58:59]
	v_lshlrev_b32_e32 v59, 16, v83
	v_lshlrev_b32_e32 v58, 16, v82
	v_pk_fma_f32 v[54:55], v[80:81], v[54:55], v[68:69]
	v_and_b32_e32 v69, 0xffff0000, v73
	v_and_b32_e32 v68, 0xffff0000, v72
	v_exp_f32_e32 v70, v70
	v_exp_f32_e32 v71, v71
	v_mul_f32_e32 v76, 0x3fb8aa3b, v58
	v_mul_f32_e32 v77, 0x3fb8aa3b, v59
	v_pk_fma_f32 v[54:55], v[54:55], v[62:63], v[68:69]
	v_and_b32_e32 v63, 0xffff0000, v79
	v_and_b32_e32 v62, 0xffff0000, v78
	v_pk_add_f32 v[48:49], v[48:49], v[58:59]
	v_lshlrev_b32_e32 v59, 16, v57
	v_lshlrev_b32_e32 v58, 16, v56
	v_exp_f32_e32 v76, v76
	v_exp_f32_e32 v77, v77
	v_pk_fma_f32 v[54:55], v[54:55], v[66:67], v[62:63]
	v_mul_f32_e32 v62, 0x3fb8aa3b, v58
	v_mul_f32_e32 v63, 0x3fb8aa3b, v59
	v_pk_add_f32 v[48:49], v[48:49], v[58:59]
	v_lshlrev_b32_e32 v59, 16, v87
	v_lshlrev_b32_e32 v58, 16, v86
	v_exp_f32_e32 v62, v62
	v_exp_f32_e32 v63, v63
	v_mul_f32_e32 v66, 0x3fb8aa3b, v58
	v_mul_f32_e32 v67, 0x3fb8aa3b, v59
	v_pk_add_f32 v[48:49], v[48:49], v[58:59]
	v_lshlrev_b32_e32 v59, 16, v61
	v_lshlrev_b32_e32 v58, 16, v60
	v_and_b32_e32 v53, 0xffff0000, v53
	v_and_b32_e32 v52, 0xffff0000, v52
	v_exp_f32_e32 v66, v66
	v_exp_f32_e32 v67, v67
	v_mul_f32_e32 v68, 0x3fb8aa3b, v58
	v_mul_f32_e32 v69, 0x3fb8aa3b, v59
	v_pk_add_f32 v[48:49], v[48:49], v[58:59]
	v_lshlrev_b32_e32 v59, 16, v91
	v_lshlrev_b32_e32 v58, 16, v90
	v_pk_fma_f32 v[52:53], v[54:55], v[70:71], v[52:53]
	v_and_b32_e32 v55, 0xffff0000, v83
	v_and_b32_e32 v54, 0xffff0000, v82
	v_exp_f32_e32 v68, v68
	v_exp_f32_e32 v69, v69
	v_mul_f32_e32 v70, 0x3fb8aa3b, v58
	v_mul_f32_e32 v71, 0x3fb8aa3b, v59
	v_lshlrev_b32_e32 v73, 16, v65
	v_lshlrev_b32_e32 v72, 16, v64
	v_exp_f32_e32 v70, v70
	v_exp_f32_e32 v71, v71
	v_pk_add_f32 v[58:59], v[48:49], v[58:59]
	v_mul_f32_e32 v48, 0x3fb8aa3b, v72
	v_mul_f32_e32 v49, 0x3fb8aa3b, v73
	v_pk_fma_f32 v[52:53], v[52:53], v[76:77], v[54:55]
	v_and_b32_e32 v55, 0xffff0000, v57
	v_and_b32_e32 v54, 0xffff0000, v56
	v_exp_f32_e32 v48, v48
	v_exp_f32_e32 v49, v49
	v_pk_fma_f32 v[52:53], v[52:53], v[62:63], v[54:55]
	v_and_b32_e32 v55, 0xffff0000, v87
	v_and_b32_e32 v54, 0xffff0000, v86
	v_pk_fma_f32 v[52:53], v[52:53], v[66:67], v[54:55]
	v_and_b32_e32 v55, 0xffff0000, v61
	v_and_b32_e32 v54, 0xffff0000, v60
	v_pk_fma_f32 v[52:53], v[52:53], v[68:69], v[54:55]
	v_and_b32_e32 v55, 0xffff0000, v91
	v_and_b32_e32 v54, 0xffff0000, v90
	v_pk_fma_f32 v[52:53], v[52:53], v[70:71], v[54:55]
	v_and_b32_e32 v55, 0xffff0000, v65
	v_and_b32_e32 v54, 0xffff0000, v64
	v_pk_fma_f32 v[48:49], v[52:53], v[48:49], v[54:55]
	v_pk_add_f32 v[54:55], v[58:59], v[72:73]
	s_waitcnt vmcnt(0)
	v_lshlrev_b32_e32 v53, 16, v115
	v_lshlrev_b32_e32 v52, 16, v114
	v_and_b32_e32 v80, 0xffff0000, v114
	v_and_b32_e32 v81, 0xffff0000, v115
	v_lshlrev_b32_e32 v83, 16, v117
	v_lshlrev_b32_e32 v82, 16, v116
	v_and_b32_e32 v86, 0xffff0000, v116
	v_and_b32_e32 v87, 0xffff0000, v117
	v_mul_f32_e32 v20, 0x3fb8aa3b, v52
	v_exp_f32_e32 v60, v20
	v_mul_f32_e32 v20, 0x3fb8aa3b, v53
	v_exp_f32_e32 v61, v20
	v_mul_f32_e32 v20, 0x3fb8aa3b, v82
	v_exp_f32_e32 v84, v20
	v_mul_f32_e32 v20, 0x3fb8aa3b, v83
	v_exp_f32_e32 v85, v20
	s_nop 0
	s_nop 0
	s_nop 0
	s_nop 0
	s_nop 0
	s_nop 0
	s_nop 0
	s_nop 0
	v_pk_add_f32 v[36:37], v[50:51], v[52:53]
	v_pk_fma_f32 v[38:39], v[38:39], v[60:61], v[80:81]
	v_pk_fma_f32 v[48:49], v[48:49], v[84:85], v[86:87]
	s_waitcnt vmcnt(9)
	v_lshlrev_b32_e32 v89, 16, v119
	v_lshlrev_b32_e32 v88, 16, v118
	v_mul_f32_e32 v50, 0x3fb8aa3b, v88
	v_mul_f32_e32 v51, 0x3fb8aa3b, v89
	v_pk_add_f32 v[36:37], v[36:37], v[88:89]
	s_waitcnt vmcnt(8)
; __device__ __forceinline__ float lo2f(uint32_t u) { return __uint_as_float(u << 16); }
; __device__ __forceinline__ void scan1_phase(const Params& p, int dir) {
;     ...
; #pragma unroll
;       for (int i = 0; i < 33; ++i) {
;         scan_step4(v[i], h);
;         as[0] += lo2f(v[i].x); as[1] += lo2f(v[i].y); as[2] += lo2f(v[i].z); as[3] += lo2f(v[i].w);
;       }
	v_lshlrev_b32_e32 v53, 16, v123
	v_lshlrev_b32_e32 v52, 16, v122
	v_exp_f32_e32 v50, v50
	v_exp_f32_e32 v51, v51
	v_mul_f32_e32 v88, 0x3fb8aa3b, v52
	v_mul_f32_e32 v89, 0x3fb8aa3b, v53
	v_pk_add_f32 v[36:37], v[36:37], v[52:53]
	s_waitcnt vmcnt(7)
	v_lshlrev_b32_e32 v53, 16, v127
	v_lshlrev_b32_e32 v52, 16, v126
	v_exp_f32_e32 v88, v88
	v_exp_f32_e32 v89, v89
	v_mul_f32_e32 v92, 0x3fb8aa3b, v52
	v_mul_f32_e32 v93, 0x3fb8aa3b, v53
	v_pk_add_f32 v[36:37], v[36:37], v[52:53]
	s_waitcnt vmcnt(6)
	v_lshlrev_b32_e32 v53, 16, v131
	v_lshlrev_b32_e32 v52, 16, v130
	v_exp_f32_e32 v92, v92
	v_exp_f32_e32 v93, v93
	v_mul_f32_e32 v94, 0x3fb8aa3b, v52
	v_mul_f32_e32 v95, 0x3fb8aa3b, v53
	v_exp_f32_e32 v94, v94
	v_exp_f32_e32 v95, v95
	v_and_b32_e32 v57, 0xffff0000, v119
	v_and_b32_e32 v56, 0xffff0000, v118
	v_pk_fma_f32 v[38:39], v[38:39], v[50:51], v[56:57]
	v_and_b32_e32 v17, 0xffff0000, v123
	v_and_b32_e32 v16, 0xffff0000, v122
	v_pk_fma_f32 v[16:17], v[38:39], v[88:89], v[16:17]
	v_and_b32_e32 v21, 0xffff0000, v127
	v_and_b32_e32 v20, 0xffff0000, v126
	v_pk_add_f32 v[36:37], v[36:37], v[52:53]
	s_waitcnt vmcnt(5)
	v_lshlrev_b32_e32 v53, 16, v135
	v_lshlrev_b32_e32 v52, 16, v134
	v_pk_fma_f32 v[16:17], v[16:17], v[92:93], v[20:21]
	v_and_b32_e32 v21, 0xffff0000, v131
	v_and_b32_e32 v20, 0xffff0000, v130
	v_mul_f32_e32 v96, 0x3fb8aa3b, v52
	v_mul_f32_e32 v97, 0x3fb8aa3b, v53
	v_pk_fma_f32 v[16:17], v[16:17], v[94:95], v[20:21]
	v_and_b32_e32 v21, 0xffff0000, v135
	v_and_b32_e32 v20, 0xffff0000, v134
	v_pk_add_f32 v[24:25], v[36:37], v[52:53]
	s_waitcnt vmcnt(4)
	v_lshlrev_b32_e32 v37, 16, v139
	v_lshlrev_b32_e32 v36, 16, v138
	v_exp_f32_e32 v96, v96
	v_exp_f32_e32 v97, v97
	v_mul_f32_e32 v38, 0x3fb8aa3b, v36
	v_mul_f32_e32 v39, 0x3fb8aa3b, v37
	v_pk_add_f32 v[24:25], v[24:25], v[36:37]
	s_waitcnt vmcnt(3)
	v_lshlrev_b32_e32 v37, 16, v143
	v_lshlrev_b32_e32 v36, 16, v142
	v_exp_f32_e32 v38, v38
	v_exp_f32_e32 v39, v39
	v_mul_f32_e32 v50, 0x3fb8aa3b, v36
	v_mul_f32_e32 v51, 0x3fb8aa3b, v37
	v_pk_add_f32 v[24:25], v[24:25], v[36:37]
	s_waitcnt vmcnt(2)
	v_lshlrev_b32_e32 v37, 16, v147
	v_lshlrev_b32_e32 v36, 16, v146
	v_exp_f32_e32 v50, v50
	v_exp_f32_e32 v51, v51
	v_mul_f32_e32 v52, 0x3fb8aa3b, v36
	v_mul_f32_e32 v53, 0x3fb8aa3b, v37
	v_pk_add_f32 v[24:25], v[24:25], v[36:37]
	s_waitcnt vmcnt(1)
	v_lshlrev_b32_e32 v37, 16, v151
	v_lshlrev_b32_e32 v36, 16, v150
	v_exp_f32_e32 v52, v52
	v_exp_f32_e32 v53, v53
	v_mul_f32_e32 v56, 0x3fb8aa3b, v36
	v_mul_f32_e32 v57, 0x3fb8aa3b, v37
	v_pk_add_f32 v[24:25], v[24:25], v[36:37]
	s_waitcnt vmcnt(0)
	v_lshlrev_b32_e32 v37, 16, v155
	v_lshlrev_b32_e32 v36, 16, v154
	v_exp_f32_e32 v56, v56
	v_exp_f32_e32 v57, v57
	v_mul_f32_e32 v60, 0x3fb8aa3b, v36
	v_mul_f32_e32 v61, 0x3fb8aa3b, v37
	v_pk_fma_f32 v[16:17], v[16:17], v[96:97], v[20:21]
	v_and_b32_e32 v21, 0xffff0000, v139
	v_and_b32_e32 v20, 0xffff0000, v138
	v_exp_f32_e32 v60, v60
	v_exp_f32_e32 v61, v61
	v_pk_fma_f32 v[16:17], v[16:17], v[38:39], v[20:21]
	v_and_b32_e32 v21, 0xffff0000, v143
	v_and_b32_e32 v20, 0xffff0000, v142
	v_pk_fma_f32 v[16:17], v[16:17], v[50:51], v[20:21]
	v_and_b32_e32 v21, 0xffff0000, v147
	v_and_b32_e32 v20, 0xffff0000, v146
	v_pk_fma_f32 v[16:17], v[16:17], v[52:53], v[20:21]
	v_and_b32_e32 v21, 0xffff0000, v151
	v_and_b32_e32 v20, 0xffff0000, v150
	v_pk_fma_f32 v[16:17], v[16:17], v[56:57], v[20:21]
	v_and_b32_e32 v21, 0xffff0000, v155
	v_and_b32_e32 v20, 0xffff0000, v154
	v_lshlrev_b32_e32 v91, 16, v121
	v_lshlrev_b32_e32 v90, 16, v120
	v_pk_fma_f32 v[52:53], v[16:17], v[60:61], v[20:21]
	v_pk_add_f32 v[16:17], v[54:55], v[82:83]
	v_pk_add_f32 v[62:63], v[24:25], v[36:37]
	v_mul_f32_e32 v20, 0x3fb8aa3b, v90
	v_mul_f32_e32 v21, 0x3fb8aa3b, v91
	v_pk_add_f32 v[16:17], v[16:17], v[90:91]
	v_lshlrev_b32_e32 v25, 16, v125
	v_lshlrev_b32_e32 v24, 16, v124
	v_exp_f32_e32 v20, v20
	v_exp_f32_e32 v21, v21
	v_mul_f32_e32 v28, 0x3fb8aa3b, v24
	v_mul_f32_e32 v29, 0x3fb8aa3b, v25
	v_pk_add_f32 v[16:17], v[16:17], v[24:25]
	v_lshlrev_b32_e32 v25, 16, v129
	v_lshlrev_b32_e32 v24, 16, v128
	v_exp_f32_e32 v28, v28
	v_exp_f32_e32 v29, v29
	v_mul_f32_e32 v32, 0x3fb8aa3b, v24
	v_mul_f32_e32 v33, 0x3fb8aa3b, v25
	v_pk_add_f32 v[16:17], v[16:17], v[24:25]
	v_lshlrev_b32_e32 v25, 16, v133
	v_lshlrev_b32_e32 v24, 16, v132
	v_exp_f32_e32 v32, v32
	v_exp_f32_e32 v33, v33
	v_mul_f32_e32 v36, 0x3fb8aa3b, v24
	v_mul_f32_e32 v37, 0x3fb8aa3b, v25
	v_exp_f32_e32 v36, v36
	v_exp_f32_e32 v37, v37
	v_and_b32_e32 v51, 0xffff0000, v121
	v_and_b32_e32 v50, 0xffff0000, v120
	v_pk_add_f32 v[16:17], v[16:17], v[24:25]
	v_lshlrev_b32_e32 v25, 16, v137
	v_lshlrev_b32_e32 v24, 16, v136
	v_pk_fma_f32 v[20:21], v[48:49], v[20:21], v[50:51]
	v_and_b32_e32 v19, 0xffff0000, v125
	v_and_b32_e32 v18, 0xffff0000, v124
	v_mul_f32_e32 v38, 0x3fb8aa3b, v24
	v_mul_f32_e32 v39, 0x3fb8aa3b, v25
	v_pk_fma_f32 v[18:19], v[20:21], v[28:29], v[18:19]
	v_and_b32_e32 v21, 0xffff0000, v129
	v_and_b32_e32 v20, 0xffff0000, v128
	v_pk_add_f32 v[16:17], v[16:17], v[24:25]
	v_lshlrev_b32_e32 v23, 16, v141
	v_lshlrev_b32_e32 v22, 16, v140
	v_exp_f32_e32 v38, v38
	v_exp_f32_e32 v39, v39
	v_pk_fma_f32 v[18:19], v[18:19], v[32:33], v[20:21]
	v_and_b32_e32 v21, 0xffff0000, v133
	v_and_b32_e32 v20, 0xffff0000, v132
	v_mul_f32_e32 v24, 0x3fb8aa3b, v22
	v_mul_f32_e32 v25, 0x3fb8aa3b, v23
	v_pk_add_f32 v[16:17], v[16:17], v[22:23]
	v_lshlrev_b32_e32 v23, 16, v145
	v_lshlrev_b32_e32 v22, 16, v144
	v_pk_fma_f32 v[18:19], v[18:19], v[36:37], v[20:21]
	v_and_b32_e32 v21, 0xffff0000, v137
	v_and_b32_e32 v20, 0xffff0000, v136
	v_exp_f32_e32 v24, v24
	v_exp_f32_e32 v25, v25
	v_mul_f32_e32 v26, 0x3fb8aa3b, v22
; __device__ __forceinline__ float lo2f(uint32_t u) { return __uint_as_float(u << 16); }
; __device__ __forceinline__ void scan1_phase(const Params& p, int dir) {
;     ...
; #pragma unroll
;       for (int i = 0; i < 33; ++i) v[i] = *(const uint4*)(RG + (rb + scan_tok(dir, pos0 + i)) * D + ch0);
; #pragma unroll
;       for (int i = 0; i < 33; ++i) {
;         scan_step4(v[i], h);
;         as[0] += lo2f(v[i].x); as[1] += lo2f(v[i].y); as[2] += lo2f(v[i].z); as[3] += lo2f(v[i].w);
;       }
;     ...
;     const size_t e = ((size_t)(b * 4 + cgp) * 264 + seg * 8 + w) * 256 + lane * 4;
	v_mul_f32_e32 v27, 0x3fb8aa3b, v23
	v_pk_add_f32 v[16:17], v[16:17], v[22:23]
	v_lshlrev_b32_e32 v23, 16, v149
	v_lshlrev_b32_e32 v22, 16, v148
	v_exp_f32_e32 v26, v26
	v_exp_f32_e32 v27, v27
	v_mul_f32_e32 v28, 0x3fb8aa3b, v22
	v_mul_f32_e32 v29, 0x3fb8aa3b, v23
	v_pk_add_f32 v[16:17], v[16:17], v[22:23]
	v_lshlrev_b32_e32 v23, 16, v153
	v_lshlrev_b32_e32 v22, 16, v152
	v_exp_f32_e32 v28, v28
	v_exp_f32_e32 v29, v29
	v_mul_f32_e32 v32, 0x3fb8aa3b, v22
	v_mul_f32_e32 v33, 0x3fb8aa3b, v23
	v_pk_add_f32 v[16:17], v[16:17], v[22:23]
	v_lshlrev_b32_e32 v23, 16, v157
	v_lshlrev_b32_e32 v22, 16, v156
	v_exp_f32_e32 v32, v32
	v_exp_f32_e32 v33, v33
	v_mul_f32_e32 v36, 0x3fb8aa3b, v22
	v_mul_f32_e32 v37, 0x3fb8aa3b, v23
	v_pk_fma_f32 v[18:19], v[18:19], v[38:39], v[20:21]
	v_and_b32_e32 v21, 0xffff0000, v141
	v_and_b32_e32 v20, 0xffff0000, v140
	v_exp_f32_e32 v36, v36
	v_exp_f32_e32 v37, v37
	v_pk_fma_f32 v[18:19], v[18:19], v[24:25], v[20:21]
	v_and_b32_e32 v21, 0xffff0000, v145
	v_and_b32_e32 v20, 0xffff0000, v144
	v_pk_fma_f32 v[18:19], v[18:19], v[26:27], v[20:21]
	v_and_b32_e32 v21, 0xffff0000, v149
	v_and_b32_e32 v20, 0xffff0000, v148
	v_pk_fma_f32 v[18:19], v[18:19], v[28:29], v[20:21]
	v_and_b32_e32 v21, 0xffff0000, v153
	v_and_b32_e32 v20, 0xffff0000, v152
	v_pk_fma_f32 v[18:19], v[18:19], v[32:33], v[20:21]
	v_and_b32_e32 v21, 0xffff0000, v157
	v_and_b32_e32 v20, 0xffff0000, v156
	v_pk_fma_f32 v[48:49], v[18:19], v[36:37], v[20:21]
	v_pk_add_f32 v[50:51], v[16:17], v[22:23]
	v_lshl_add_u64 v[2:3], s[30:31], 0, v[40:41]
	s_waitcnt vmcnt(1)
	v_lshlrev_b32_e32 v72, 16, v158
	v_lshlrev_b32_e32 v73, 16, v159
	v_mul_f32_e32 v6, 0x3fb8aa3b, v72
	v_exp_f32_e32 v68, v6
	v_mul_f32_e32 v6, 0x3fb8aa3b, v73
	v_lshlrev_b32_e32 v64, 16, v160
	v_exp_f32_e32 v69, v6
	v_lshlrev_b32_e32 v65, 16, v161
	v_mul_f32_e32 v6, 0x3fb8aa3b, v64
	v_exp_f32_e32 v58, v6
	v_mul_f32_e32 v6, 0x3fb8aa3b, v65
	v_exp_f32_e32 v59, v6
	v_mov_b32_e32 v6, 0x108
	v_mad_i64_i32 v[2:3], s[4:5], s3, v6, v[2:3]
	v_and_b32_e32 v70, 0xffff0000, v158
	v_and_b32_e32 v71, 0xffff0000, v159
	v_and_b32_e32 v60, 0xffff0000, v160
	v_and_b32_e32 v61, 0xffff0000, v161
	v_lshlrev_b64 v[54:55], 10, v[2:3]
	s_nop 0
	s_nop 0
	s_waitcnt vmcnt(9)
	v_lshlrev_b32_e32 v77, 16, v179
	v_lshlrev_b32_e32 v76, 16, v178
	v_pk_add_f32 v[44:45], v[62:63], v[72:73]
	v_mul_f32_e32 v42, 0x3fb8aa3b, v76
	v_mul_f32_e32 v43, 0x3fb8aa3b, v77
	v_pk_add_f32 v[44:45], v[44:45], v[76:77]
	v_exp_f32_e32 v42, v42
	v_exp_f32_e32 v43, v43
	v_pk_fma_f32 v[52:53], v[52:53], v[68:69], v[70:71]
	v_and_b32_e32 v25, 0xffff0000, v179
	v_and_b32_e32 v24, 0xffff0000, v178
	v_pk_fma_f32 v[24:25], v[52:53], v[42:43], v[24:25]
	v_lshlrev_b32_e32 v66, 16, v180
	v_lshlrev_b32_e32 v67, 16, v181
	v_pk_fma_f32 v[48:49], v[48:49], v[58:59], v[60:61]
	v_and_b32_e32 v27, 0xffff0000, v181
	v_and_b32_e32 v26, 0xffff0000, v180
	v_or_b32_e32 v54, v54, v75
	v_lshl_add_u64 v[56:57], s[44:45], 0, v[54:55]
	s_waitcnt vmcnt(8)
	v_lshlrev_b32_e32 v47, 16, v183
	v_lshlrev_b32_e32 v46, 16, v182
	v_mul_f32_e32 v62, 0x3fb8aa3b, v46
	v_mul_f32_e32 v63, 0x3fb8aa3b, v47
	v_pk_add_f32 v[44:45], v[44:45], v[46:47]
	s_waitcnt vmcnt(7)
	v_lshlrev_b32_e32 v47, 16, v187
	v_lshlrev_b32_e32 v46, 16, v186
	v_exp_f32_e32 v62, v62
	v_exp_f32_e32 v63, v63
	v_mul_f32_e32 v72, 0x3fb8aa3b, v46
	v_mul_f32_e32 v73, 0x3fb8aa3b, v47
	v_pk_add_f32 v[44:45], v[44:45], v[46:47]
	s_waitcnt vmcnt(6)
	v_lshlrev_b32_e32 v47, 16, v191
	v_lshlrev_b32_e32 v46, 16, v190
	v_exp_f32_e32 v72, v72
	v_exp_f32_e32 v73, v73
	v_mul_f32_e32 v76, 0x3fb8aa3b, v46
	v_mul_f32_e32 v77, 0x3fb8aa3b, v47
	v_exp_f32_e32 v76, v76
	v_exp_f32_e32 v77, v77
	v_and_b32_e32 v37, 0xffff0000, v183
	v_and_b32_e32 v36, 0xffff0000, v182
	v_pk_fma_f32 v[24:25], v[24:25], v[62:63], v[36:37]
	v_and_b32_e32 v33, 0xffff0000, v187
	v_and_b32_e32 v32, 0xffff0000, v186
	v_pk_add_f32 v[46:47], v[44:45], v[46:47]
	s_waitcnt vmcnt(5)
	v_lshlrev_b32_e32 v79, 16, v195
	v_lshlrev_b32_e32 v78, 16, v194
	v_pk_fma_f32 v[24:25], v[24:25], v[72:73], v[32:33]
	v_and_b32_e32 v29, 0xffff0000, v191
	v_and_b32_e32 v28, 0xffff0000, v190
	v_pk_fma_f32 v[52:53], v[24:25], v[76:77], v[28:29]
	v_and_b32_e32 v63, 0xffff0000, v195
	v_and_b32_e32 v62, 0xffff0000, v194
	v_pk_add_f32 v[20:21], v[46:47], v[78:79]
	s_waitcnt vmcnt(4)
	v_lshlrev_b32_e32 v29, 16, v199
	v_lshlrev_b32_e32 v28, 16, v198
	v_pk_add_f32 v[20:21], v[20:21], v[28:29]
	s_waitcnt vmcnt(3)
	v_lshlrev_b32_e32 v33, 16, v203
	v_lshlrev_b32_e32 v32, 16, v202
	v_pk_add_f32 v[20:21], v[20:21], v[32:33]
	s_waitcnt vmcnt(2)
	v_lshlrev_b32_e32 v37, 16, v207
	v_lshlrev_b32_e32 v36, 16, v206
	v_pk_add_f32 v[20:21], v[20:21], v[36:37]
	s_waitcnt vmcnt(1)
	v_lshlrev_b32_e32 v43, 16, v211
	v_lshlrev_b32_e32 v42, 16, v210
	v_pk_add_f32 v[20:21], v[20:21], v[42:43]
	s_waitcnt vmcnt(0)
; __device__ __forceinline__ float lo2f(uint32_t u) { return __uint_as_float(u << 16); }
; __device__ __forceinline__ void scan1_phase(const Params& p, int dir) {
;     ...
; #pragma unroll
;       for (int i = 0; i < 33; ++i) {
;         scan_step4(v[i], h);
;         as[0] += lo2f(v[i].x); as[1] += lo2f(v[i].y); as[2] += lo2f(v[i].z); as[3] += lo2f(v[i].w);
;       }
;     }
;     const size_t e = ((size_t)(b * 4 + cgp) * 264 + seg * 8 + w) * 256 + lane * 4;
;     *(float4*)(suma + e) = make_float4(as[0], as[1], as[2], as[3]);
;     *(float4*)(sumh + e) = make_float4(h[0], h[1], h[2], h[3]);
	v_lshlrev_b32_e32 v47, 16, v237
	v_lshlrev_b32_e32 v46, 16, v236
	v_mul_f32_e32 v24, 0x3fb8aa3b, v28
	v_mul_f32_e32 v25, 0x3fb8aa3b, v29
	v_mul_f32_e32 v28, 0x3fb8aa3b, v32
	v_mul_f32_e32 v29, 0x3fb8aa3b, v33
	v_mul_f32_e32 v32, 0x3fb8aa3b, v36
	v_mul_f32_e32 v33, 0x3fb8aa3b, v37
	v_mul_f32_e32 v36, 0x3fb8aa3b, v42
	v_mul_f32_e32 v37, 0x3fb8aa3b, v43
	v_mul_f32_e32 v42, 0x3fb8aa3b, v46
	v_mul_f32_e32 v43, 0x3fb8aa3b, v47
	v_pk_add_f32 v[20:21], v[20:21], v[46:47]
	v_pk_add_f32 v[46:47], v[50:51], v[64:65]
	v_mul_f32_e32 v50, 0x3fb8aa3b, v66
	v_exp_f32_e32 v68, v50
	v_mul_f32_e32 v50, 0x3fb8aa3b, v67
	v_exp_f32_e32 v69, v50
	v_lshlrev_b32_e32 v50, 16, v184
	v_pk_add_f32 v[46:47], v[46:47], v[66:67]
	v_lshlrev_b32_e32 v51, 16, v185
	v_mul_f32_e32 v64, 0x3fb8aa3b, v50
	v_exp_f32_e32 v72, v64
	v_mul_f32_e32 v64, 0x3fb8aa3b, v51
	v_pk_add_f32 v[46:47], v[46:47], v[50:51]
	v_lshlrev_b32_e32 v50, 16, v188
	v_exp_f32_e32 v73, v64
	v_lshlrev_b32_e32 v51, 16, v189
	v_mul_f32_e32 v64, 0x3fb8aa3b, v50
	v_exp_f32_e32 v70, v64
	v_mul_f32_e32 v64, 0x3fb8aa3b, v51
	v_pk_add_f32 v[46:47], v[46:47], v[50:51]
	v_lshlrev_b32_e32 v50, 16, v192
	v_exp_f32_e32 v71, v64
	v_lshlrev_b32_e32 v51, 16, v193
	v_mul_f32_e32 v64, 0x3fb8aa3b, v50
	v_exp_f32_e32 v66, v64
	v_mul_f32_e32 v64, 0x3fb8aa3b, v51
	v_exp_f32_e32 v67, v64
	v_pk_fma_f32 v[26:27], v[48:49], v[68:69], v[26:27]
	v_and_b32_e32 v39, 0xffff0000, v185
	v_and_b32_e32 v38, 0xffff0000, v184
	v_pk_fma_f32 v[26:27], v[26:27], v[72:73], v[38:39]
	v_and_b32_e32 v35, 0xffff0000, v189
	v_and_b32_e32 v34, 0xffff0000, v188
	v_pk_fma_f32 v[26:27], v[26:27], v[70:71], v[34:35]
	v_and_b32_e32 v31, 0xffff0000, v193
	v_and_b32_e32 v30, 0xffff0000, v192
	v_pk_add_f32 v[50:51], v[46:47], v[50:51]
	v_lshlrev_b32_e32 v65, 16, v197
	v_lshlrev_b32_e32 v64, 16, v196
	v_pk_fma_f32 v[58:59], v[26:27], v[66:67], v[30:31]
	v_lshlrev_b32_e32 v26, 16, v200
	v_and_b32_e32 v61, 0xffff0000, v197
	v_and_b32_e32 v60, 0xffff0000, v196
	v_pk_add_f32 v[22:23], v[50:51], v[64:65]
	v_lshlrev_b32_e32 v27, 16, v201
	v_mul_f32_e32 v30, 0x3fb8aa3b, v26
	v_exp_f32_e32 v48, v30
	v_mul_f32_e32 v30, 0x3fb8aa3b, v27
	v_pk_add_f32 v[22:23], v[22:23], v[26:27]
	v_lshlrev_b32_e32 v26, 16, v204
	v_exp_f32_e32 v49, v30
	v_lshlrev_b32_e32 v27, 16, v205
	v_mul_f32_e32 v30, 0x3fb8aa3b, v26
	v_mul_f32_e32 v44, 0x3fb8aa3b, v78
	v_mul_f32_e32 v45, 0x3fb8aa3b, v79
	v_exp_f32_e32 v38, v30
	v_mul_f32_e32 v30, 0x3fb8aa3b, v27
	v_pk_add_f32 v[22:23], v[22:23], v[26:27]
	v_lshlrev_b32_e32 v26, 16, v208
	v_exp_f32_e32 v44, v44
	v_exp_f32_e32 v45, v45
	v_exp_f32_e32 v39, v30
	v_lshlrev_b32_e32 v27, 16, v209
	v_mul_f32_e32 v30, 0x3fb8aa3b, v26
	v_exp_f32_e32 v24, v24
	v_exp_f32_e32 v25, v25
	v_exp_f32_e32 v34, v30
	v_mul_f32_e32 v30, 0x3fb8aa3b, v27
	v_pk_add_f32 v[22:23], v[22:23], v[26:27]
	v_lshlrev_b32_e32 v27, 16, v213
	v_lshlrev_b32_e32 v26, 16, v212
	v_exp_f32_e32 v28, v28
	v_exp_f32_e32 v29, v29
	v_pk_add_f32 v[22:23], v[22:23], v[26:27]
	v_lshlrev_b32_e32 v51, 16, v239
	v_lshlrev_b32_e32 v50, 16, v238
	v_exp_f32_e32 v32, v32
	v_exp_f32_e32 v33, v33
	v_pk_add_f32 v[22:23], v[22:23], v[50:51]
	v_exp_f32_e32 v36, v36
	v_exp_f32_e32 v37, v37
	v_mul_f32_e32 v46, 0x3fb8aa3b, v64
	v_mul_f32_e32 v47, 0x3fb8aa3b, v65
	global_store_dwordx4 v[56:57], v[20:23], off
	v_and_b32_e32 v17, 0xffff0000, v199
	v_and_b32_e32 v16, 0xffff0000, v198
	v_pk_fma_f32 v[22:23], v[52:53], v[44:45], v[62:63]
	v_exp_f32_e32 v42, v42
	v_exp_f32_e32 v43, v43
	v_exp_f32_e32 v46, v46
	v_exp_f32_e32 v47, v47
	v_pk_fma_f32 v[16:17], v[22:23], v[24:25], v[16:17]
	v_and_b32_e32 v13, 0xffff0000, v203
	v_and_b32_e32 v12, 0xffff0000, v202
	v_pk_fma_f32 v[12:13], v[16:17], v[28:29], v[12:13]
	v_and_b32_e32 v9, 0xffff0000, v207
	v_and_b32_e32 v8, 0xffff0000, v206
	v_pk_fma_f32 v[8:9], v[12:13], v[32:33], v[8:9]
	v_and_b32_e32 v5, 0xffff0000, v211
	v_and_b32_e32 v4, 0xffff0000, v210
	v_exp_f32_e32 v35, v30
	v_mul_f32_e32 v30, 0x3fb8aa3b, v26
	v_mul_f32_e32 v31, 0x3fb8aa3b, v27
	v_pk_fma_f32 v[4:5], v[8:9], v[36:37], v[4:5]
	v_and_b32_e32 v1, 0xffff0000, v237
	v_and_b32_e32 v0, 0xffff0000, v236
	v_exp_f32_e32 v30, v30
	v_exp_f32_e32 v31, v31
	v_mul_f32_e32 v26, 0x3fb8aa3b, v50
	v_mul_f32_e32 v27, 0x3fb8aa3b, v51
	v_pk_fma_f32 v[0:1], v[4:5], v[42:43], v[0:1]
	v_pk_fma_f32 v[4:5], v[58:59], v[46:47], v[60:61]
	v_and_b32_e32 v9, 0xffff0000, v201
	v_and_b32_e32 v8, 0xffff0000, v200
	v_exp_f32_e32 v26, v26
	v_exp_f32_e32 v27, v27
	v_pk_fma_f32 v[4:5], v[4:5], v[48:49], v[8:9]
	v_and_b32_e32 v9, 0xffff0000, v205
	v_and_b32_e32 v8, 0xffff0000, v204
	v_pk_fma_f32 v[4:5], v[4:5], v[38:39], v[8:9]
	v_and_b32_e32 v9, 0xffff0000, v209
	v_and_b32_e32 v8, 0xffff0000, v208
	v_pk_fma_f32 v[4:5], v[4:5], v[34:35], v[8:9]
	v_and_b32_e32 v7, 0xffff0000, v213
	v_and_b32_e32 v6, 0xffff0000, v212
	v_pk_fma_f32 v[4:5], v[4:5], v[30:31], v[6:7]
	v_and_b32_e32 v3, 0xffff0000, v239
	v_and_b32_e32 v2, 0xffff0000, v238
	v_lshl_add_u64 v[20:21], s[46:47], 0, v[54:55]
	v_pk_fma_f32 v[2:3], v[4:5], v[26:27], v[2:3]
	global_store_dwordx4 v[20:21], v[0:3], off
	s_cbranch_scc0 .LBB0_145
